# meta-row skinny GEMM loops: all k-step loads issued up front with counted vmcnt (7 loops), on top of attention setprio
# baseline (speedup 1.0000x reference)
.LBB0_384:
	s_waitcnt lgkmcnt(0)
	global_load_dwordx4 v[136:139], v[10:11], off
	global_load_dwordx4 v[140:143], v[12:13], off
	global_load_dwordx4 v[144:147], v[8:9], off
	global_load_dwordx4 v[148:151], v[10:11], off offset:512
	global_load_dwordx4 v[152:155], v[12:13], off offset:512
	global_load_dwordx4 v[156:159], v[8:9], off offset:512
	global_load_dwordx4 v[168:171], v[10:11], off offset:1024
	global_load_dwordx4 v[172:175], v[12:13], off offset:1024
	global_load_dwordx4 v[176:179], v[8:9], off offset:1024
	global_load_dwordx4 v[180:183], v[10:11], off offset:1536
	global_load_dwordx4 v[184:187], v[12:13], off offset:1536
	global_load_dwordx4 v[198:201], v[8:9], off offset:1536
	s_waitcnt vmcnt(9)
	v_mfma_f32_16x16x32_bf16 v[0:3], v[136:139], v[140:143], v[0:3]
	v_mfma_f32_16x16x32_bf16 v[4:7], v[144:147], v[140:143], v[4:7]
	s_waitcnt vmcnt(6)
	v_mfma_f32_16x16x32_bf16 v[0:3], v[148:151], v[152:155], v[0:3]
	v_mfma_f32_16x16x32_bf16 v[4:7], v[156:159], v[152:155], v[4:7]
	s_waitcnt vmcnt(3)
	v_mfma_f32_16x16x32_bf16 v[0:3], v[168:171], v[172:175], v[0:3]
	v_mfma_f32_16x16x32_bf16 v[4:7], v[176:179], v[172:175], v[4:7]
	s_waitcnt vmcnt(0)
	v_mfma_f32_16x16x32_bf16 v[0:3], v[180:183], v[184:187], v[0:3]
	v_mfma_f32_16x16x32_bf16 v[4:7], v[198:201], v[184:187], v[4:7]
	s_nop 7

.LBB0_412:
	global_load_dwordx4 v[138:141], v[18:19], off
	global_load_dwordx4 v[148:151], v[20:21], off
	global_load_dwordx4 v[152:155], v[16:17], off
	global_load_dwordx4 v[156:159], v[18:19], off offset:512
	global_load_dwordx4 v[160:163], v[20:21], off offset:512
	global_load_dwordx4 v[164:167], v[16:17], off offset:512
	global_load_dwordx4 v[168:171], v[18:19], off offset:1024
	global_load_dwordx4 v[172:175], v[20:21], off offset:1024
	global_load_dwordx4 v[176:179], v[16:17], off offset:1024
	global_load_dwordx4 v[180:183], v[18:19], off offset:1536
	global_load_dwordx4 v[184:187], v[20:21], off offset:1536
	global_load_dwordx4 v[188:191], v[16:17], off offset:1536
	s_waitcnt vmcnt(9)
	v_mfma_f32_16x16x32_bf16 v[0:3], v[138:141], v[148:151], v[0:3]
	v_mfma_f32_16x16x32_bf16 v[4:7], v[152:155], v[148:151], v[4:7]
	s_waitcnt vmcnt(6)
	v_mfma_f32_16x16x32_bf16 v[0:3], v[156:159], v[160:163], v[0:3]
	v_mfma_f32_16x16x32_bf16 v[4:7], v[164:167], v[160:163], v[4:7]
	s_waitcnt vmcnt(3)
	v_mfma_f32_16x16x32_bf16 v[0:3], v[168:171], v[172:175], v[0:3]
	v_mfma_f32_16x16x32_bf16 v[4:7], v[176:179], v[172:175], v[4:7]
	s_waitcnt vmcnt(0)
	v_mfma_f32_16x16x32_bf16 v[0:3], v[180:183], v[184:187], v[0:3]
	v_mfma_f32_16x16x32_bf16 v[4:7], v[188:191], v[184:187], v[4:7]
	s_nop 7

.LBB0_1665:
	global_load_dwordx4 v[128:131], v[16:17], off
	global_load_dwordx4 v[132:135], v[18:19], off
	global_load_dwordx4 v[136:139], v[14:15], off
	global_load_dwordx4 v[140:143], v[16:17], off offset:512
	global_load_dwordx4 v[144:147], v[18:19], off offset:512
	global_load_dwordx4 v[148:151], v[14:15], off offset:512
	global_load_dwordx4 v[152:155], v[16:17], off offset:1024
	global_load_dwordx4 v[156:159], v[18:19], off offset:1024
	global_load_dwordx4 v[160:163], v[14:15], off offset:1024
	global_load_dwordx4 v[164:167], v[16:17], off offset:1536
	global_load_dwordx4 v[168:171], v[18:19], off offset:1536
	global_load_dwordx4 v[172:175], v[14:15], off offset:1536
	global_load_dwordx4 v[176:179], v[16:17], off offset:2048
	global_load_dwordx4 v[180:183], v[18:19], off offset:2048
	global_load_dwordx4 v[184:187], v[14:15], off offset:2048
	global_load_dwordx4 v[188:191], v[16:17], off offset:2560
	global_load_dwordx4 v[26:29], v[18:19], off offset:2560
	global_load_dwordx4 v[30:33], v[14:15], off offset:2560
	s_waitcnt vmcnt(15)
	v_mfma_f32_16x16x32_bf16 v[0:3], v[128:131], v[132:135], v[0:3]
	v_mfma_f32_16x16x32_bf16 v[4:7], v[136:139], v[132:135], v[4:7]
	global_load_dwordx4 v[128:131], v[16:17], off offset:3072
	global_load_dwordx4 v[132:135], v[18:19], off offset:3072
	global_load_dwordx4 v[136:139], v[14:15], off offset:3072
	s_waitcnt vmcnt(15)
	v_mfma_f32_16x16x32_bf16 v[0:3], v[140:143], v[144:147], v[0:3]
	v_mfma_f32_16x16x32_bf16 v[4:7], v[148:151], v[144:147], v[4:7]
	global_load_dwordx4 v[140:143], v[16:17], off offset:3584
	global_load_dwordx4 v[144:147], v[18:19], off offset:3584
	global_load_dwordx4 v[148:151], v[14:15], off offset:3584
	s_waitcnt vmcnt(15)
	v_mfma_f32_16x16x32_bf16 v[0:3], v[152:155], v[156:159], v[0:3]
	v_mfma_f32_16x16x32_bf16 v[4:7], v[160:163], v[156:159], v[4:7]
	v_add_co_u32_e32 v16, vcc, 0x1000, v16
	s_nop 1
	v_addc_co_u32_e32 v17, vcc, 0, v17, vcc
	v_add_co_u32_e32 v18, vcc, 0x1000, v18
	s_nop 1
	v_addc_co_u32_e32 v19, vcc, 0, v19, vcc
	v_add_co_u32_e32 v14, vcc, 0x1000, v14
	s_nop 1
	v_addc_co_u32_e32 v15, vcc, 0, v15, vcc
	global_load_dwordx4 v[152:155], v[16:17], off
	global_load_dwordx4 v[156:159], v[18:19], off
	global_load_dwordx4 v[160:163], v[14:15], off
	s_waitcnt vmcnt(15)
	v_mfma_f32_16x16x32_bf16 v[0:3], v[164:167], v[168:171], v[0:3]
	v_mfma_f32_16x16x32_bf16 v[4:7], v[172:175], v[168:171], v[4:7]
	global_load_dwordx4 v[164:167], v[16:17], off offset:512
	global_load_dwordx4 v[168:171], v[18:19], off offset:512
	global_load_dwordx4 v[172:175], v[14:15], off offset:512
	s_waitcnt vmcnt(15)
	v_mfma_f32_16x16x32_bf16 v[0:3], v[176:179], v[180:183], v[0:3]
	v_mfma_f32_16x16x32_bf16 v[4:7], v[184:187], v[180:183], v[4:7]
	global_load_dwordx4 v[176:179], v[16:17], off offset:1024
	global_load_dwordx4 v[180:183], v[18:19], off offset:1024
	global_load_dwordx4 v[184:187], v[14:15], off offset:1024
	s_waitcnt vmcnt(15)
	v_mfma_f32_16x16x32_bf16 v[0:3], v[188:191], v[26:29], v[0:3]
	v_mfma_f32_16x16x32_bf16 v[4:7], v[30:33], v[26:29], v[4:7]
	s_waitcnt vmcnt(12)
	v_mfma_f32_16x16x32_bf16 v[0:3], v[128:131], v[132:135], v[0:3]
	v_mfma_f32_16x16x32_bf16 v[4:7], v[136:139], v[132:135], v[4:7]
	s_waitcnt vmcnt(9)
	v_mfma_f32_16x16x32_bf16 v[0:3], v[140:143], v[144:147], v[0:3]
	v_mfma_f32_16x16x32_bf16 v[4:7], v[148:151], v[144:147], v[4:7]
	s_waitcnt vmcnt(6)
	v_mfma_f32_16x16x32_bf16 v[0:3], v[152:155], v[156:159], v[0:3]
	v_mfma_f32_16x16x32_bf16 v[4:7], v[160:163], v[156:159], v[4:7]
	s_waitcnt vmcnt(3)
	v_mfma_f32_16x16x32_bf16 v[0:3], v[164:167], v[168:171], v[0:3]
	v_mfma_f32_16x16x32_bf16 v[4:7], v[172:175], v[168:171], v[4:7]
	s_waitcnt vmcnt(0)
	v_mfma_f32_16x16x32_bf16 v[0:3], v[176:179], v[180:183], v[0:3]
	v_mfma_f32_16x16x32_bf16 v[4:7], v[184:187], v[180:183], v[4:7]
	s_nop 7

.LBB0_2074:
	global_load_dwordx4 v[136:139], v[10:11], off
	global_load_dwordx4 v[140:143], v[12:13], off
	global_load_dwordx4 v[144:147], v[8:9], off
	s_waitcnt vmcnt(0)
	v_mfma_f32_16x16x32_bf16 v[0:3], v[136:139], v[140:143], v[0:3]
	v_mfma_f32_16x16x32_bf16 v[4:7], v[144:147], v[140:143], v[4:7]
	s_nop 7

.LBB0_2740:
	global_load_dwordx4 v[144:147], v[18:19], off
	global_load_dwordx4 v[148:151], v[22:23], off
	global_load_dwordx4 v[152:155], v[20:21], off
	s_waitcnt vmcnt(0)
	v_mfma_f32_16x16x32_bf16 v[0:3], v[144:147], v[148:151], v[0:3]
	v_mfma_f32_16x16x32_bf16 v[4:7], v[152:155], v[148:151], v[4:7]
	s_nop 7

.LBB0_2814:
	global_load_dwordx4 v[138:141], v[18:19], off
	global_load_dwordx4 v[142:145], v[20:21], off
	global_load_dwordx4 v[146:149], v[16:17], off
	global_load_dwordx4 v[154:157], v[18:19], off offset:512
	global_load_dwordx4 v[158:161], v[20:21], off offset:512
	global_load_dwordx4 v[162:165], v[16:17], off offset:512
	global_load_dwordx4 v[166:169], v[18:19], off offset:1024
	global_load_dwordx4 v[170:173], v[20:21], off offset:1024
	global_load_dwordx4 v[174:177], v[16:17], off offset:1024
	global_load_dwordx4 v[178:181], v[18:19], off offset:1536
	global_load_dwordx4 v[182:185], v[20:21], off offset:1536
	global_load_dwordx4 v[186:189], v[16:17], off offset:1536
	s_waitcnt vmcnt(9)
	v_mfma_f32_16x16x32_bf16 v[0:3], v[138:141], v[142:145], v[0:3]
	v_mfma_f32_16x16x32_bf16 v[4:7], v[146:149], v[142:145], v[4:7]
	s_waitcnt vmcnt(6)
	v_mfma_f32_16x16x32_bf16 v[0:3], v[154:157], v[158:161], v[0:3]
	v_mfma_f32_16x16x32_bf16 v[4:7], v[162:165], v[158:161], v[4:7]
	s_waitcnt vmcnt(3)
	v_mfma_f32_16x16x32_bf16 v[0:3], v[166:169], v[170:173], v[0:3]
	v_mfma_f32_16x16x32_bf16 v[4:7], v[174:177], v[170:173], v[4:7]
	s_waitcnt vmcnt(0)
	v_mfma_f32_16x16x32_bf16 v[0:3], v[178:181], v[182:185], v[0:3]
	v_mfma_f32_16x16x32_bf16 v[4:7], v[186:189], v[182:185], v[4:7]
	s_nop 7
